# peel + epilogue-start vmcnt(8) + HGRN loop-header vmcnt(16): waits no longer drain unrelated stores/prefetches
# speedup vs baseline: 1.0075x; 1.0036x over previous
; #define GAS __attribute__((address_space(1)))
; __device__ __forceinline__ void hgrn_phase(const Params& p, int e, char* lds) {
;     ...
;   for (int u = blockIdx.x; u < 256; u += gridDim.x) {
;     const int kh = u & 1, dir = (u >> 1) & 1, h = (u >> 2) & 3, b = u >> 4;
;     float lbk = 0.f;
;     if (e != 0) { const float* lbsrc = dir ? p.lb_bwd : p.lb_fwd; const float a0 = lbsrc[h * 128 + kh * 64 + k], a1 = lbsrc[512 + h * 128 + kh * 64 + k]; lbk = 1.0f / (1.0f + __expf(a0 - a1)); }
;     const int rsb = dir ? -8192 : 8192;
;     const int base0 = (b * SEQ + (dir ? (SEQ - 1) : 0)) * 8192;
;     const int qcol = (1536 + h * 128 + kh * 64 + lc8) * 2, zcol = ((dir ? 2560 : 2048) + h * 128 + kh * 64 + lc8) * 2, vcol = (3072 + h * 128 + vc8) * 2;
;     const int osb = dir ? -1024 : 1024;
;     const int obase = (dir * 2 + kh) * (T * 1024) + (b * SEQ + (dir ? (SEQ - 1) : 0)) * 1024 + h * 256;
;     f32x4 Sacc[4];
; #pragma unroll
;     for (int i = 0; i < 4; ++i) Sacc[i] = (f32x4){0.f, 0.f, 0.f, 0.f};
;     for (int i = tid; i < 128 * PK / 16; i += 512) *(u32x4*)(ST + i * 16) = (u32x4){0, 0, 0, 0};
;     u32x4 gq, gz, gv0, gv1;
;     { const int o0 = base0 + rsb * lr;
;       gq = *(const GAS u32x4*)(bigc + (size_t)(unsigned)(o0 + qcol)); gz = *(const GAS u32x4*)(bigc + (size_t)(unsigned)(o0 + zcol));
;       gv0 = *(const GAS u32x4*)(bigc + (size_t)(unsigned)(base0 + rsb * vr + vcol)); gv1 = *(const GAS u32x4*)(bigc + (size_t)(unsigned)(base0 + rsb * (vr + 32) + vcol)); }
.LBB0_220:
	s_or_b64 exec, exec, s[26:27]
	s_lshl_b32 s20, s36, 8
	s_lshr_b32 s26, s36, 2
	s_and_b32 s20, s20, 0xfffff000
	s_cmp_eq_u32 s8, 0
	s_movk_i32 s8, 0xa00
	s_cselect_b32 s21, 0, 0xfff
	s_cselect_b32 s8, 0x800, s8
	s_movk_i32 s27, 0xe000
	s_movk_i32 s34, 0xfc00
	s_cselect_b32 s27, 0x2000, s27
	s_cselect_b32 s34, 0x400, s34
	s_or_b32 s35, s21, s20
	s_or_b32 s20, s8, s12
	v_or_b32_e32 v2, s10, v106
	v_mov_b32_e32 v3, 0x1800
	v_or_b32_e32 v1, s20, v104
	v_lshl_add_u32 v2, v2, 1, v3
	s_lshl_b32 s8, s35, 13
	v_mul_lo_u32 v3, s27, v103
	v_add_lshl_u32 v0, s14, v104, 1
	v_or_b32_e32 v1, s10, v1
	v_add_u32_e32 v3, s8, v3
	s_movk_i32 s10, 0xc00
	v_add3_u32 v0, v0, v3, s10
	v_lshl_or_b32 v1, v1, 1, v3
	global_load_dwordx4 v[16:19], v0, s[30:31]
	global_load_dwordx4 v[20:23], v1, s[30:31]
	v_mul_lo_u32 v0, s27, v105
	s_lshl_b32 s10, s27, 5
	v_add3_u32 v1, s8, v0, v2
	s_add_i32 s8, s8, s10
	v_add3_u32 v0, s8, v0, v2
	global_load_dwordx4 v[24:27], v1, s[30:31]
	global_load_dwordx4 v[28:31], v0, s[30:31]
	s_and_b32 s8, s26, 3
	s_lshl_b32 vcc_hi, s8, 8
	s_lshr_b32 s8, s2, 12
	s_lshl_b32 s26, s8, 22
	s_lshl_b32 s5, s21, 10
	s_and_b32 s12, s39, 0xc000000
	v_mul_lo_u32 v0, v132, s34
	s_or_b32 s5, s5, s26
	v_or_b32_e32 v0, v131, v0
	s_add_i32 s5, s5, s12
	v_add_u32_e32 v164, s5, v0
	v_mul_lo_u32 v0, v113, s34
	v_or_b32_e32 v0, v131, v0
	v_add_u32_e32 v165, s5, v0
	v_mul_lo_u32 v0, v114, s34
	v_or_b32_e32 v0, v131, v0
	v_add_u32_e32 v166, s5, v0
	v_mul_lo_u32 v0, v112, s34
	v_or_b32_e32 v0, v131, v0
	s_lshl_b32 s8, s8, 25
	v_add_u32_e32 v167, s5, v0
	v_mul_lo_u32 v0, v134, s27
	s_lshl_b32 s5, s21, 13
	v_or_b32_e32 v0, v133, v0
	s_or_b32 s21, s5, s8
	v_add_u32_e32 v168, s21, v0
	v_mul_lo_u32 v0, v135, s27
	v_or_b32_e32 v0, v133, v0
	v_add_u32_e32 v169, s21, v0
	v_mul_lo_u32 v0, v137, s27
	s_lshl_b32 s14, s14, 1
	s_lshl_b32 s20, s20, 1
	v_add_u32_e32 v170, s5, v0
	s_or_b32 s21, vcc_hi, s8
	v_or_b32_e32 v0, v138, v0
	s_add_i32 s14, s14, s5
	s_add_i32 s21, s21, s20
	v_add_u32_e32 v172, s14, v0
	v_mov_b32_e32 v0, 0
	s_mov_b32 vcc_lo, 0
	v_sub_f32_e32 v163, 1.0, v162
	s_lshl_b32 s10, s27, 6
	s_lshl_b32 s12, s34, 6
	v_add_u32_e32 v171, s21, v136
	v_mov_b32_e32 v1, v0
	v_mov_b32_e32 v2, v0
	v_mov_b32_e32 v3, v0
	v_mov_b32_e32 v4, v0
	v_mov_b32_e32 v5, v0
	v_mov_b32_e32 v6, v0
	v_mov_b32_e32 v7, v0
	v_mov_b32_e32 v12, v0
	v_mov_b32_e32 v13, v0
	v_mov_b32_e32 v14, v0
	v_mov_b32_e32 v15, v0
	v_mov_b32_e32 v8, v0
	v_mov_b32_e32 v9, v0
	v_mov_b32_e32 v10, v0
	v_mov_b32_e32 v11, v0
	s_waitcnt vmcnt(0)
	s_branch .LBB0_222

; __device__ __forceinline__ void hgrn_phase(const Params& p, int e, char* lds) {
;     ...
;     for (int c = 0; c < SEQ / 64; ++c) {
;       const int pb = c & 1;
;       *(u32x4*)(RQ + lr * PK + lc8 * 2) = gq; *(u32x4*)(RZ + lr * PK + lc8 * 2) = gz;
;       *(u32x4*)(RV + vr * PV + vc8 * 2) = gv0; *(u32x4*)(RV + (vr + 32) * PV + vc8 * 2) = gv1;
;       LBAR();
;       float qf[8], kk[8], cl[8]; float run = 0.f;
; #pragma unroll
;       for (int i = 0; i < 8; ++i) { const int t = 8 * rq + i; const float z = bf2f(*(const unsigned short*)(RZ + t * PK + k * 2)); qf[i] = bf2f(*(const unsigned short*)(RQ + t * PK + k * 2));
;         const float sg = __builtin_amdgcn_rcpf(1.0f + __builtin_amdgcn_exp2f(-L2E * z)); const float f = lbk + (1.0f - lbk) * sg;
;         run += __builtin_amdgcn_logf(f); cl[i] = run; kk[i] = 1.0f - f; }
;       TOT[rq * 64 + k] = run;
;       unsigned short rvv[16];
; #pragma unroll
;       for (int i = 0; i < 16; ++i) rvv[i] = *(const unsigned short*)(RV + (16 * jg + i) * PV + vv * 2);
;       u32x4 vpa, vpb;
;       vpa.x = rvv[0] | ((unsigned)rvv[1] << 16); vpa.y = rvv[2] | ((unsigned)rvv[3] << 16); vpa.z = rvv[4] | ((unsigned)rvv[5] << 16); vpa.w = rvv[6] | ((unsigned)rvv[7] << 16);
;       vpb.x = rvv[8] | ((unsigned)rvv[9] << 16); vpb.y = rvv[10] | ((unsigned)rvv[11] << 16); vpb.z = rvv[12] | ((unsigned)rvv[13] << 16); vpb.w = rvv[14] | ((unsigned)rvv[15] << 16);
;       LBAR();
;       { float tt[8];
; #pragma unroll
;         for (int r8 = 0; r8 < 8; ++r8) tt[r8] = TOT[r8 * 64 + k];
;         const float mid = (tt[0] + tt[1]) + (tt[2] + tt[3]), last = mid + ((tt[4] + tt[5]) + (tt[6] + tt[7]));
;         float off = 0.f;
; #pragma unroll
;         for (int r8 = 0; r8 < 7; ++r8) off += (r8 < rq) ? tt[r8] : 0.f;
;         const float el = __builtin_amdgcn_exp2f(last), em = __builtin_amdgcn_exp2f(fminf(-mid, 120.f)), emi = __builtin_amdgcn_exp2f(mid);
;         if (rq == 0) DD[k] = el;
;         unsigned ksw[4];
; #pragma unroll
;         for (int i = 0; i < 8; ++i) { const float cc = off + cl[i];
;           const float e1 = __builtin_amdgcn_exp2f(cc), inv1 = __builtin_amdgcn_exp2f(fminf(-cc, 120.f));
;           const float ea = fminf(e1 * em, 3.6e16f), eb = fminf(inv1 * emi, 3.6e16f), es = fminf(inv1 * el, 1.0f);
;           const int t = 8 * rq + i;
.LBB0_222:
	s_waitcnt vmcnt(16)
	ds_write_b128 v143, v[16:19]
	ds_write_b128 v143, v[20:23] offset:9216
	ds_write_b128 v152, v[24:27] offset:18432
	ds_write_b128 v152, v[28:31] offset:27136
	s_waitcnt lgkmcnt(0)
	s_barrier
	ds_read_u16 v16, v100 offset:9216
	ds_read_u16 v17, v100 offset:9360
	ds_read_u16 v18, v100 offset:9504
	ds_read_u16 v19, v100 offset:9648
	ds_read_u16 v20, v100 offset:9792
	ds_read_u16 v21, v100 offset:9936
	ds_read_u16 v22, v100 offset:10080
	ds_read_u16 v23, v100 offset:10224
	s_waitcnt lgkmcnt(6)
	v_lshlrev_b32_e32 v17, 16, v17
	v_mul_f32_e32 v17, 0xbfb8aa3b, v17
	v_exp_f32_e32 v17, v17
	v_lshlrev_b32_e32 v16, 16, v16
	v_mul_f32_e32 v16, 0xbfb8aa3b, v16
	s_waitcnt lgkmcnt(5)
	v_lshlrev_b32_e32 v18, 16, v18
	v_exp_f32_e32 v16, v16
	v_add_f32_e32 v17, 1.0, v17
	v_mul_f32_e32 v18, 0xbfb8aa3b, v18
	v_rcp_f32_e32 v17, v17
	v_exp_f32_e32 v18, v18
	v_add_f32_e32 v16, 1.0, v16
	v_rcp_f32_e32 v16, v16
	v_fma_f32 v33, v163, v17, v162
	v_add_f32_e32 v17, 1.0, v18
	s_waitcnt lgkmcnt(4)
	v_lshlrev_b32_e32 v18, 16, v19
	v_mul_f32_e32 v18, 0xbfb8aa3b, v18
	v_rcp_f32_e32 v17, v17
	v_exp_f32_e32 v18, v18
	v_fma_f32 v32, v163, v16, v162
	v_log_f32_e32 v16, v32
	v_log_f32_e32 v19, v33
	v_fma_f32 v34, v163, v17, v162
	v_add_f32_e32 v18, 1.0, v18
	v_log_f32_e32 v17, v34
	v_rcp_f32_e32 v18, v18
	v_add_f32_e32 v31, 0, v16
	v_add_f32_e32 v30, v31, v19
	v_add_f32_e32 v29, v30, v17
	v_fma_f32 v37, v163, v18, v162
	s_waitcnt lgkmcnt(3)
	v_lshlrev_b32_e32 v17, 16, v20
	s_waitcnt lgkmcnt(2)
	v_lshlrev_b32_e32 v18, 16, v21
	v_mul_f32_e32 v17, 0xbfb8aa3b, v17
	v_mul_f32_e32 v18, 0xbfb8aa3b, v18
	v_log_f32_e32 v16, v37
	v_exp_f32_e32 v17, v17
	v_exp_f32_e32 v18, v18
	ds_read_u16 v57, v100
	ds_read_u16 v55, v100 offset:144
	ds_read_u16 v54, v100 offset:288
	ds_read_u16 v52, v100 offset:432
	ds_read_u16 v50, v100 offset:576
	ds_read_u16 v49, v100 offset:720
	ds_read_u16 v47, v100 offset:864
	ds_read_u16 v45, v100 offset:1008
	v_add_f32_e32 v27, v29, v16
	v_add_f32_e32 v16, 1.0, v17
	v_add_f32_e32 v17, 1.0, v18
	s_waitcnt lgkmcnt(9)
	v_lshlrev_b32_e32 v18, 16, v22
	v_mul_f32_e32 v18, 0xbfb8aa3b, v18
	v_rcp_f32_e32 v17, v17
	v_exp_f32_e32 v18, v18
	v_rcp_f32_e32 v16, v16
	v_fma_f32 v39, v163, v17, v162
	v_add_f32_e32 v17, 1.0, v18
	s_waitcnt lgkmcnt(8)
	v_lshlrev_b32_e32 v18, 16, v23
	v_mul_f32_e32 v18, 0xbfb8aa3b, v18
	v_exp_f32_e32 v18, v18
	v_rcp_f32_e32 v17, v17
	v_fma_f32 v38, v163, v16, v162
	v_log_f32_e32 v16, v38
	v_add_f32_e32 v18, 1.0, v18
	v_rcp_f32_e32 v18, v18
	v_log_f32_e32 v19, v39
	v_fma_f32 v40, v163, v17, v162
	v_log_f32_e32 v17, v40
	v_fma_f32 v41, v163, v18, v162
	v_add_f32_e32 v28, v27, v16
	v_log_f32_e32 v16, v41
	v_add_f32_e32 v26, v28, v19
	v_add_f32_e32 v25, v26, v17
	v_add_f32_e32 v24, v25, v16
	ds_write_b32 v107, v24
	ds_read_u16 v35, v153 offset:18432
	ds_read_u16 v36, v153 offset:18704
	ds_read_u16 v43, v153 offset:18976
	ds_read_u16 v44, v153 offset:19248
	ds_read_u16 v46, v153 offset:19520
	ds_read_u16 v48, v153 offset:19792
	ds_read_u16 v51, v153 offset:20064
	ds_read_u16 v53, v153 offset:20336
	ds_read_u16 v56, v153 offset:20608
	ds_read_u16 v58, v153 offset:20880
	ds_read_u16 v59, v153 offset:21152
	ds_read_u16 v60, v153 offset:21424
	ds_read_u16 v61, v153 offset:21696
	ds_read_u16 v62, v153 offset:21968
	ds_read_u16 v63, v153 offset:22240
	ds_read_u16 v64, v153 offset:22512
	s_waitcnt lgkmcnt(0)
	s_barrier
	ds_read2st64_b32 v[20:21], v108 offset0:2 offset1:3
	ds_read2st64_b32 v[18:19], v108 offset0:4 offset1:5
	ds_read2st64_b32 v[16:17], v108 offset0:6 offset1:7
	ds_read2st64_b32 v[22:23], v108 offset1:1
	s_waitcnt lgkmcnt(3)
	v_add_f32_e32 v42, v20, v21
	s_waitcnt lgkmcnt(2)
	v_add_f32_e32 v65, v18, v19
	s_waitcnt lgkmcnt(1)
	v_add_f32_e32 v17, v16, v17
	v_add_f32_e32 v17, v65, v17
	s_waitcnt lgkmcnt(0)
	v_add_f32_e32 v65, v22, v23
	v_add_f32_e32 v42, v65, v42
	v_add_f32_e32 v17, v42, v17
	v_exp_f32_e32 v17, v17
	s_and_saveexec_b64 s[26:27], s[42:43]
	ds_write_b32 v109, v17
	s_or_b64 exec, exec, s[26:27]
	v_add_f32_e32 v22, 0, v22
	v_cndmask_b32_e64 v22, 0, v22, s[64:65]
	v_cndmask_b32_e64 v23, 0, v23, s[66:67]
	v_add_f32_e32 v22, v22, v23
	v_cndmask_b32_e64 v20, 0, v20, s[68:69]
	v_add_f32_e32 v20, v22, v20
	v_cndmask_b32_e64 v21, 0, v21, s[70:71]
	v_add_f32_e32 v20, v20, v21
	v_cndmask_b32_e64 v18, 0, v18, s[72:73]
	v_add_f32_e32 v18, v20, v18
	v_cndmask_b32_e64 v19, 0, v19, s[74:75]
	v_add_f32_e32 v18, v18, v19
	v_cndmask_b32_e64 v16, 0, v16, s[76:77]
	v_add_f32_e32 v16, v18, v16
	v_max_f32_e64 v18, -v42, -v42
	v_min_f32_e32 v18, 0x42f00000, v18
	v_exp_f32_e32 v21, v18
	v_add_f32_e32 v18, v31, v16
	v_exp_f32_e32 v19, v18
	v_min_f32_e64 v18, -v18, s33
	v_exp_f32_e32 v22, v42
	v_exp_f32_e32 v18, v18
	v_lshlrev_b32_e32 v57, 16, v57
	v_mul_f32_e32 v20, v21, v19
	v_sub_f32_e32 v32, 1.0, v32
	v_mul_f32_e32 v23, v22, v18
	v_mul_f32_e32 v18, v17, v18
	v_min_f32_e32 v20, 0x5affcb9e, v20
	v_min_f32_e32 v18, 1.0, v18
	v_mul_f32_e32 v19, v19, v57
	v_min_f32_e32 v23, 0x5affcb9e, v23
	v_mul_f32_e32 v20, v20, v57
	v_cvt_pk_bf16_f32 v19, v19, v20
	v_mul_f32_e32 v18, v32, v18
	v_mul_f32_e32 v20, v32, v23
	v_cvt_pk_bf16_f32 v18, v20, v18
	ds_write_b16 v100, v19
	ds_write_b16_d16_hi v100, v19 offset:9216
	ds_write_b16 v100, v18 offset:18432
	v_add_f32_e32 v19, v30, v16
	v_exp_f32_e32 v20, v19
	v_min_f32_e64 v19, -v19, s33
	v_exp_f32_e32 v19, v19
	v_lshlrev_b32_e32 v55, 16, v55
	v_mul_f32_e32 v23, v21, v20
	v_sub_f32_e32 v33, 1.0, v33
	v_mul_f32_e32 v30, v22, v19
	v_mul_f32_e32 v19, v17, v19
	v_min_f32_e32 v23, 0x5affcb9e, v23
	v_min_f32_e32 v19, 1.0, v19
	v_mul_f32_e32 v20, v20, v55
	v_min_f32_e32 v30, 0x5affcb9e, v30
; #define GAS __attribute__((address_space(1)))
; __device__ __forceinline__ void hgrn_phase(const Params& p, int e, char* lds) {
;     ...
;         for (int i = 0; i < 8; ++i) { const float cc = off + cl[i];
;           const float e1 = __builtin_amdgcn_exp2f(cc), inv1 = __builtin_amdgcn_exp2f(fminf(-cc, 120.f));
;           const float ea = fminf(e1 * em, 3.6e16f), eb = fminf(inv1 * emi, 3.6e16f), es = fminf(inv1 * el, 1.0f);
;           const int t = 8 * rq + i;
;           const unsigned w0 = cvtpk(qf[i] * e1, qf[i] * ea), w1 = cvtpk(kk[i] * eb, kk[i] * es);
;           *(unsigned short*)(QD + t * PK + k * 2) = (unsigned short)(w0 & 0xffffu);
;           *(unsigned short*)(QA + t * PK + k * 2) = (unsigned short)(w0 >> 16);
;           *(unsigned short*)(KB + t * PK + k * 2) = (unsigned short)(w1 & 0xffffu);
;           if (i & 1) ksw[i >> 1] |= (w1 & 0xffff0000u); else ksw[i >> 1] = (w1 >> 16); }
;         *(u32x4*)(KS + k * PJ + rq * 16) = (u32x4){ksw[0], ksw[1], ksw[2], ksw[3]};
;         *(u32x4*)(VT + vv * PJ + jg * 32) = vpa; *(u32x4*)(VT + vv * PJ + jg * 32 + 16) = vpb; }
;       LBAR();
;       if (c + 1 < SEQ / 64) { const int bc = base0 + rsb * 64 * (c + 1); const int o0 = bc + rsb * lr;
;         gq = *(const GAS u32x4*)(bigc + (size_t)(unsigned)(o0 + qcol)); gz = *(const GAS u32x4*)(bigc + (size_t)(unsigned)(o0 + zcol));
;         gv0 = *(const GAS u32x4*)(bigc + (size_t)(unsigned)(bc + rsb * vr + vcol)); gv1 = *(const GAS u32x4*)(bigc + (size_t)(unsigned)(bc + rsb * (vr + 32) + vcol)); }
;     ...
;       f32x4 oacc[4];
;       const int wq = wave >> 1, vt0 = 4 * (wave & 1);
;       { const int ttA = 2 * (wave & 1); const char* STp = ST + pb * (128 * PK);
;         bf16x8 fa[2], fb0[2], fb1[2], fqd[2], fs[4][2];
; #pragma unroll
;         for (int ks = 0; ks < 2; ++ks) { fa[ks] = ldfrag(KB, 16 * wq + fr, PK, ks * 32 + fq_ * 8); fb0[ks] = ldfrag(QA, 16 * ttA + fr, PK, ks * 32 + fq_ * 8); fb1[ks] = ldfrag(QA, 16 * (ttA + 1) + fr, PK, ks * 32 + fq_ * 8);
;           fqd[ks] = ldfrag(QD, 16 * wq + fr, PK, ks * 32 + fq_ * 8);
; #pragma unroll
;           for (int n = 0; n < 4; ++n) fs[n][ks] = ldfrag(STp, 16 * (vt0 + n) + fr, PK, ks * 32 + fq_ * 8); }
;         HWAIT();
;         f32x4 acc0 = (f32x4){0.f, 0.f, 0.f, 0.f}, acc1 = acc0;
; #pragma unroll
;         for (int n = 0; n < 4; ++n) oacc[n] = acc0;
; #pragma unroll
;         for (int ks = 0; ks < 2; ++ks) {
	v_mul_f32_e32 v23, v23, v55
	v_cvt_pk_bf16_f32 v20, v20, v23
	v_mul_f32_e32 v19, v33, v19
	v_mul_f32_e32 v23, v33, v30
	v_cvt_pk_bf16_f32 v19, v23, v19
	ds_write_b16 v100, v20 offset:144
	ds_write_b16_d16_hi v100, v20 offset:9360
	ds_write_b16 v100, v19 offset:18576
	v_add_f32_e32 v20, v29, v16
	v_exp_f32_e32 v23, v20
	v_min_f32_e64 v20, -v20, s33
	v_exp_f32_e32 v20, v20
	v_lshrrev_b32_e32 v18, 16, v18
	v_and_or_b32 v18, v19, s13, v18
	v_mul_f32_e32 v19, v21, v23
	v_lshlrev_b32_e32 v54, 16, v54
	v_min_f32_e32 v19, 0x5affcb9e, v19
	v_mul_f32_e32 v29, v22, v20
	v_mul_f32_e32 v20, v17, v20
	v_sub_f32_e32 v34, 1.0, v34
	v_min_f32_e32 v20, 1.0, v20
	v_mul_f32_e32 v19, v19, v54
	v_min_f32_e32 v29, 0x5affcb9e, v29
	v_mul_f32_e32 v23, v23, v54
	v_cvt_pk_bf16_f32 v19, v23, v19
	v_mul_f32_e32 v20, v34, v20
	v_mul_f32_e32 v23, v34, v29
	v_cvt_pk_bf16_f32 v20, v23, v20
	ds_write_b16 v100, v19 offset:288
	ds_write_b16_d16_hi v100, v19 offset:9504
	ds_write_b16 v100, v20 offset:18720
	v_add_f32_e32 v19, v27, v16
	v_exp_f32_e32 v23, v19
	v_min_f32_e64 v19, -v19, s33
	v_exp_f32_e32 v19, v19
	v_lshlrev_b32_e32 v52, 16, v52
	v_mul_f32_e32 v27, v21, v23
	v_sub_f32_e32 v37, 1.0, v37
	v_mul_f32_e32 v29, v22, v19
	v_mul_f32_e32 v19, v17, v19
	v_min_f32_e32 v27, 0x5affcb9e, v27
	v_min_f32_e32 v19, 1.0, v19
	v_mul_f32_e32 v23, v23, v52
	v_min_f32_e32 v29, 0x5affcb9e, v29
	v_mul_f32_e32 v27, v27, v52
	v_cvt_pk_bf16_f32 v23, v23, v27
	v_mul_f32_e32 v19, v37, v19
	v_mul_f32_e32 v27, v37, v29
	v_cvt_pk_bf16_f32 v19, v27, v19
	ds_write_b16 v100, v23 offset:432
	ds_write_b16_d16_hi v100, v23 offset:9648
	ds_write_b16 v100, v19 offset:18864
	v_add_f32_e32 v23, v28, v16
	v_exp_f32_e32 v27, v23
	v_min_f32_e64 v23, -v23, s33
	v_exp_f32_e32 v23, v23
	v_lshrrev_b32_e32 v20, 16, v20
	v_and_or_b32 v19, v19, s13, v20
	v_mul_f32_e32 v20, v21, v27
	v_lshlrev_b32_e32 v50, 16, v50
	v_min_f32_e32 v20, 0x5affcb9e, v20
	v_mul_f32_e32 v28, v22, v23
	v_mul_f32_e32 v23, v17, v23
	v_sub_f32_e32 v65, 1.0, v38
	v_min_f32_e32 v23, 1.0, v23
	v_mul_f32_e32 v20, v20, v50
	v_min_f32_e32 v28, 0x5affcb9e, v28
	v_mul_f32_e32 v27, v27, v50
	v_cvt_pk_bf16_f32 v20, v27, v20
	v_mul_f32_e32 v23, v65, v23
	v_mul_f32_e32 v27, v65, v28
	v_cvt_pk_bf16_f32 v23, v27, v23
	ds_write_b16 v100, v20 offset:576
	ds_write_b16_d16_hi v100, v20 offset:9792
	ds_write_b16 v100, v23 offset:19008
	v_add_f32_e32 v20, v26, v16
	v_exp_f32_e32 v26, v20
	v_min_f32_e64 v20, -v20, s33
	v_exp_f32_e32 v20, v20
	v_lshlrev_b32_e32 v49, 16, v49
	v_mul_f32_e32 v27, v21, v26
	v_sub_f32_e32 v66, 1.0, v39
	v_mul_f32_e32 v28, v22, v20
	v_mul_f32_e32 v20, v17, v20
	v_min_f32_e32 v27, 0x5affcb9e, v27
	v_min_f32_e32 v20, 1.0, v20
	v_mul_f32_e32 v26, v26, v49
	v_min_f32_e32 v28, 0x5affcb9e, v28
	v_mul_f32_e32 v27, v27, v49
	v_cvt_pk_bf16_f32 v26, v26, v27
	v_mul_f32_e32 v20, v66, v20
	v_add_f32_e32 v25, v25, v16
	v_mul_f32_e32 v27, v66, v28
	v_cvt_pk_bf16_f32 v20, v27, v20
	ds_write_b16 v100, v26 offset:720
	ds_write_b16_d16_hi v100, v26 offset:9936
	ds_write_b16 v100, v20 offset:19152
	v_exp_f32_e32 v26, v25
	v_min_f32_e64 v25, -v25, s33
	v_exp_f32_e32 v25, v25
	v_lshrrev_b32_e32 v23, 16, v23
	v_and_or_b32 v20, v20, s13, v23
	v_mul_f32_e32 v23, v21, v26
	v_lshlrev_b32_e32 v67, 16, v47
	v_min_f32_e32 v23, 0x5affcb9e, v23
	v_mul_f32_e32 v27, v22, v25
	v_mul_f32_e32 v25, v17, v25
	v_sub_f32_e32 v68, 1.0, v40
	v_min_f32_e32 v25, 1.0, v25
	v_mul_f32_e32 v23, v23, v67
	v_min_f32_e32 v27, 0x5affcb9e, v27
	v_mul_f32_e32 v26, v26, v67
	v_cvt_pk_bf16_f32 v23, v26, v23
	v_mul_f32_e32 v25, v68, v25
	v_add_f32_e32 v16, v24, v16
	v_mul_f32_e32 v26, v68, v27
	v_cvt_pk_bf16_f32 v25, v26, v25
	ds_write_b16 v100, v23 offset:864
	ds_write_b16_d16_hi v100, v23 offset:10080
	ds_write_b16 v100, v25 offset:19296
	v_exp_f32_e32 v23, v16
	v_min_f32_e64 v16, -v16, s33
	v_exp_f32_e32 v16, v16
	v_lshlrev_b32_e32 v69, 16, v45
	v_mul_f32_e32 v21, v21, v23
	v_min_f32_e32 v21, 0x5affcb9e, v21
	v_mul_f32_e32 v22, v22, v16
	v_mul_f32_e32 v16, v17, v16
	v_sub_f32_e32 v70, 1.0, v41
	v_min_f32_e32 v22, 0x5affcb9e, v22
	v_min_f32_e32 v16, 1.0, v16
	v_mul_f32_e32 v17, v23, v69
	v_mul_f32_e32 v21, v21, v69
	v_lshrrev_b32_e32 v24, 16, v25
	v_cvt_pk_bf16_f32 v17, v17, v21
	v_mul_f32_e32 v21, v70, v22
	v_mul_f32_e32 v16, v70, v16
	v_cvt_pk_bf16_f32 v16, v21, v16
	v_perm_b32 v41, v64, v63, s7
	v_and_or_b32 v21, v16, s13, v24
	v_perm_b32 v40, v62, v61, s7
	v_perm_b32 v39, v60, v59, s7
	v_perm_b32 v38, v58, v56, s7
	v_perm_b32 v47, v53, v51, s7
	v_perm_b32 v46, v48, v46, s7
	v_perm_b32 v45, v44, v43, s7
	v_perm_b32 v44, v36, v35, s7
	ds_write_b16 v100, v17 offset:1008
	ds_write_b16_d16_hi v100, v17 offset:10224
	ds_write_b16 v100, v16 offset:19440
	ds_write_b128 v154, v[18:21] offset:27648
	ds_write_b128 v155, v[44:47] offset:36864
	ds_write_b128 v155, v[38:41] offset:36880
	s_waitcnt lgkmcnt(0)
	s_barrier
	v_add_u32_e32 v16, s8, v172
	v_add_u32_e32 v20, v171, v170
	v_add_u32_e32 v24, vcc_hi, v169
	v_add_u32_e32 v28, vcc_hi, v168
	global_load_dwordx4 v[16:19], v16, s[30:31]
	s_nop 0
	global_load_dwordx4 v[20:23], v20, s[30:31]
	s_nop 0
	global_load_dwordx4 v[24:27], v24, s[30:31]
	s_nop 0
	global_load_dwordx4 v[28:31], v28, s[30:31]
	s_and_b32 s14, vcc_lo, 1
	s_mul_i32 s5, s14, 0x4800
	v_add_u32_e32 v32, s5, v122
	v_add_u32_e32 v36, v32, v101
	v_add_u32_e32 v37, v32, v119
	v_add_u32_e32 v38, v32, v120
	v_add_u32_e32 v39, v32, v121
	v_add_u32_e32 v173, v111, v110
	ds_read_b128 v[76:79], v156 offset:18432
	ds_read_b128 v[56:59], v156 offset:18496
	ds_read_b128 v[52:55], v173 offset:9216
	ds_read_b128 v[68:71], v173 offset:9280
	ds_read_b128 v[84:87], v173 offset:11520
	ds_read_b128 v[64:67], v173 offset:11584
	ds_read_b128 v[72:75], v156
	ds_read_b128 v[32:35], v156 offset:64
	ds_read_b128 v[80:83], v36 offset:64512
	ds_read_b128 v[48:51], v36 offset:64576
	ds_read_b128 v[88:91], v37 offset:64512
	ds_read_b128 v[44:47], v37 offset:64576
	ds_read_b128 v[92:95], v38 offset:64512
	ds_read_b128 v[40:43], v38 offset:64576
	ds_read_b128 v[96:99], v39 offset:64512
	ds_read_b128 v[36:39], v39 offset:64576
	s_waitcnt lgkmcnt(0)
	v_mov_b32_e32 v145, v144
	v_mov_b32_e32 v146, v144
	v_mov_b32_e32 v147, v144
	v_mov_b64_e32 v[60:61], v[144:145]
	v_mov_b64_e32 v[62:63], v[146:147]
	s_and_saveexec_b64 s[26:27], s[44:45]
	s_cbranch_execz .LBB0_226
	s_waitcnt lgkmcnt(13)
	v_mfma_f32_16x16x32_bf16 v[60:63], v[76:79], v[52:55], 0
